# stacked+ : v38 plus P7 residual epilogue with base loads two row-groups ahead and P1 two rows per trip
# baseline (speedup 1.0000x reference)
;     __device__ __forceinline__ void operator()(const f32x4 (&acc)[2][2][4][2], const Unit& u, int wr, int wc, int fr, int fq) const {
;         const int row0 = u.pm * BM + wr * 64 + fr, col0 = u.pn * BM + wc * 32 + 8 * fq; const int b = (u.pm * BM) / SEQ;
;         f32x4 gv[2][2];
; #pragma unroll
;         for (int bj = 0; bj < 2; ++bj)
; #pragma unroll
;             for (int n = 0; n < 2; ++n) gv[bj][n] = *(const f32x4*)(gate + (size_t)b * gate_ld + col0 + bj * HALF + 4 * n);
; #pragma unroll
;         for (int ai = 0; ai < 2; ++ai)
; #pragma unroll
;             for (int m = 0; m < 4; ++m) { const size_t ro = (size_t)(row0 + ai * HALF + m * 16) * DM + col0;
; #pragma unroll
;                 for (int bj = 0; bj < 2; ++bj) { f32x4 b0, b1;
;                     if (BASE_F32) { b0 = *(const f32x4*)((const float*)base + ro + bj * HALF); b1 = *(const f32x4*)((const float*)base + ro + bj * HALF + 4); }
;                     else { const half8 hb = *(const half8*)((const h16*)base + ro + bj * HALF);
;                            b0 = (f32x4){(float)hb[0], (float)hb[1], (float)hb[2], (float)hb[3]}; b1 = (f32x4){(float)hb[4], (float)hb[5], (float)hb[6], (float)hb[7]}; }
;                     const f32x4 v0 = b0 + gv[bj][0] * acc[ai][bj][m][0], v1 = b1 + gv[bj][1] * acc[ai][bj][m][1];
;                     u32x4 w; w.x = pk_h2(v0[0], v0[1]); w.y = pk_h2(v0[2], v0[3]); w.z = pk_h2(v1[0], v1[1]); w.w = pk_h2(v1[2], v1[3]);
;                     *(u32x4*)(out + ro + bj * HALF) = w; } }
.LBB0_715:
	s_ashr_i32 s35, s42, 31
	s_lshr_b32 s35, s35, 27
	s_add_i32 s35, s42, s35
	s_ashr_i32 s35, s35, 5
	v_lshl_add_u32 v180, s42, 8, v164
	v_lshl_or_b32 v178, s59, 8, v166
	s_mul_hi_i32 s37, s35, 0xc000
	s_mul_i32 s35, s35, 0xc000
	v_ashrrev_i32_e32 v181, 31, v180
	s_add_u32 s44, s52, s35
	v_ashrrev_i32_e32 v179, 31, v178
	v_lshlrev_b64 v[134:135], 11, v[180:181]
	s_addc_u32 s45, s53, s37
	v_lshl_add_u64 v[162:163], v[134:135], 0, v[178:179]
	v_lshl_add_u64 v[138:139], v[178:179], 2, s[44:45]
	v_lshl_add_u64 v[182:183], v[162:163], 2, s[6:7]
	s_andn2_b64 vcc, exec, s[4:5]
	s_mov_b64 s[4:5], -1
	s_mov_b64 s[98:99], 0x20000
	s_mov_b64 s[100:101], 0x10000
	global_load_dwordx4 v[130:133], v[138:139], off
	global_load_dwordx4 v[142:145], v[138:139], off offset:16
	global_load_dwordx4 v[134:137], v[138:139], off offset:528
	s_nop 0
	global_load_dwordx4 v[138:141], v[138:139], off offset:512
	v_lshl_add_u64 v[184:185], v[162:163], 1, s[10:11]
	global_load_dwordx4 v[186:189], v[182:183], off
	global_load_dwordx4 v[190:193], v[182:183], off offset:16
	global_load_dwordx4 v[194:197], v[182:183], off offset:512
	global_load_dwordx4 v[198:201], v[182:183], off offset:528
	v_lshl_add_u64 v[182:183], v[182:183], 0, s[98:99]
	global_load_dwordx4 v[202:205], v[182:183], off
	global_load_dwordx4 v[206:209], v[182:183], off offset:16
	global_load_dwordx4 v[210:213], v[182:183], off offset:512
	global_load_dwordx4 v[214:217], v[182:183], off offset:528
	s_waitcnt vmcnt(4)
	v_pk_fma_f32 v[128:129], v[128:129], v[132:133], v[188:189]
	v_pk_fma_f32 v[126:127], v[126:127], v[130:131], v[186:187]
	v_pk_fma_f32 v[124:125], v[124:125], v[144:145], v[192:193]
	v_pk_fma_f32 v[122:123], v[122:123], v[142:143], v[190:191]
	v_cvt_pk_f16_f32 v126, v126, v127
	v_cvt_pk_f16_f32 v127, v128, v129
	v_cvt_pk_f16_f32 v128, v122, v123
	v_cvt_pk_f16_f32 v129, v124, v125
	global_store_dwordx4 v[184:185], v[126:129], off
	v_pk_fma_f32 v[120:121], v[120:121], v[140:141], v[196:197]
	v_pk_fma_f32 v[118:119], v[118:119], v[138:139], v[194:195]
	v_pk_fma_f32 v[116:117], v[116:117], v[136:137], v[200:201]
	v_pk_fma_f32 v[114:115], v[114:115], v[134:135], v[198:199]
	v_cvt_pk_f16_f32 v118, v118, v119
	v_cvt_pk_f16_f32 v119, v120, v121
	v_cvt_pk_f16_f32 v120, v114, v115
	v_cvt_pk_f16_f32 v121, v116, v117
	global_store_dwordx4 v[184:185], v[118:121], off offset:256
	v_lshl_add_u64 v[182:183], v[182:183], 0, s[98:99]
	global_load_dwordx4 v[126:129], v[182:183], off
	global_load_dwordx4 v[122:125], v[182:183], off offset:16
	global_load_dwordx4 v[118:121], v[182:183], off offset:512
	global_load_dwordx4 v[114:117], v[182:183], off offset:528
	s_waitcnt vmcnt(6)
	v_lshl_add_u64 v[184:185], v[184:185], 0, s[100:101]
	v_pk_fma_f32 v[112:113], v[112:113], v[132:133], v[204:205]
	v_pk_fma_f32 v[110:111], v[110:111], v[130:131], v[202:203]
	v_pk_fma_f32 v[108:109], v[108:109], v[144:145], v[208:209]
	v_pk_fma_f32 v[106:107], v[106:107], v[142:143], v[206:207]
	v_cvt_pk_f16_f32 v110, v110, v111
	v_cvt_pk_f16_f32 v111, v112, v113
	v_cvt_pk_f16_f32 v112, v106, v107
	v_cvt_pk_f16_f32 v113, v108, v109
	global_store_dwordx4 v[184:185], v[110:113], off
	v_pk_fma_f32 v[104:105], v[104:105], v[140:141], v[212:213]
	v_pk_fma_f32 v[102:103], v[102:103], v[138:139], v[210:211]
	v_pk_fma_f32 v[100:101], v[100:101], v[136:137], v[216:217]
	v_pk_fma_f32 v[98:99], v[98:99], v[134:135], v[214:215]
	v_cvt_pk_f16_f32 v102, v102, v103
	v_cvt_pk_f16_f32 v103, v104, v105
	v_cvt_pk_f16_f32 v104, v98, v99
	v_cvt_pk_f16_f32 v105, v100, v101
	global_store_dwordx4 v[184:185], v[102:105], off offset:256
	v_lshl_add_u64 v[182:183], v[182:183], 0, s[98:99]
	global_load_dwordx4 v[110:113], v[182:183], off
	global_load_dwordx4 v[106:109], v[182:183], off offset:16
	global_load_dwordx4 v[102:105], v[182:183], off offset:512
	global_load_dwordx4 v[98:101], v[182:183], off offset:528
	s_waitcnt vmcnt(6)
	v_lshl_add_u64 v[184:185], v[184:185], 0, s[100:101]
	v_pk_fma_f32 v[96:97], v[96:97], v[132:133], v[128:129]
	v_pk_fma_f32 v[94:95], v[94:95], v[130:131], v[126:127]
	v_pk_fma_f32 v[92:93], v[92:93], v[144:145], v[124:125]
	v_pk_fma_f32 v[90:91], v[90:91], v[142:143], v[122:123]
	v_cvt_pk_f16_f32 v94, v94, v95
	v_cvt_pk_f16_f32 v95, v96, v97
	v_cvt_pk_f16_f32 v96, v90, v91
	v_cvt_pk_f16_f32 v97, v92, v93
	global_store_dwordx4 v[184:185], v[94:97], off
	v_pk_fma_f32 v[88:89], v[88:89], v[140:141], v[120:121]
	v_pk_fma_f32 v[86:87], v[86:87], v[138:139], v[118:119]
	v_pk_fma_f32 v[84:85], v[84:85], v[136:137], v[116:117]
	v_pk_fma_f32 v[82:83], v[82:83], v[134:135], v[114:115]
	v_cvt_pk_f16_f32 v86, v86, v87
	v_cvt_pk_f16_f32 v87, v88, v89
	v_cvt_pk_f16_f32 v88, v82, v83
	v_cvt_pk_f16_f32 v89, v84, v85
	global_store_dwordx4 v[184:185], v[86:89], off offset:256
	v_lshl_add_u64 v[182:183], v[182:183], 0, s[98:99]
	v_lshl_add_u64 v[182:183], v[182:183], 0, s[98:99]
	v_lshl_add_u64 v[182:183], v[182:183], 0, s[98:99]
	v_lshl_add_u64 v[182:183], v[182:183], 0, s[98:99]
	v_lshl_add_u64 v[182:183], v[182:183], 0, s[98:99]
	global_load_dwordx4 v[94:97], v[182:183], off
	global_load_dwordx4 v[90:93], v[182:183], off offset:16
	global_load_dwordx4 v[86:89], v[182:183], off offset:512
	global_load_dwordx4 v[82:85], v[182:183], off offset:528
	s_waitcnt vmcnt(6)
;     __device__ __forceinline__ void operator()(const f32x4 (&acc)[2][2][4][2], const Unit& u, int wr, int wc, int fr, int fq) const {
;         const int row0 = u.pm * BM + wr * 64 + fr, col0 = u.pn * BM + wc * 32 + 8 * fq; const int b = (u.pm * BM) / SEQ;
;         f32x4 gv[2][2];
; #pragma unroll
;         for (int bj = 0; bj < 2; ++bj)
; #pragma unroll
;             for (int n = 0; n < 2; ++n) gv[bj][n] = *(const f32x4*)(gate + (size_t)b * gate_ld + col0 + bj * HALF + 4 * n);
; #pragma unroll
;         for (int ai = 0; ai < 2; ++ai)
; #pragma unroll
;             for (int m = 0; m < 4; ++m) { const size_t ro = (size_t)(row0 + ai * HALF + m * 16) * DM + col0;
; #pragma unroll
;                 for (int bj = 0; bj < 2; ++bj) { f32x4 b0, b1;
;                     if (BASE_F32) { b0 = *(const f32x4*)((const float*)base + ro + bj * HALF); b1 = *(const f32x4*)((const float*)base + ro + bj * HALF + 4); }
;                     else { const half8 hb = *(const half8*)((const h16*)base + ro + bj * HALF);
;                            b0 = (f32x4){(float)hb[0], (float)hb[1], (float)hb[2], (float)hb[3]}; b1 = (f32x4){(float)hb[4], (float)hb[5], (float)hb[6], (float)hb[7]}; }
;                     const f32x4 v0 = b0 + gv[bj][0] * acc[ai][bj][m][0], v1 = b1 + gv[bj][1] * acc[ai][bj][m][1];
;                     u32x4 w; w.x = pk_h2(v0[0], v0[1]); w.y = pk_h2(v0[2], v0[3]); w.z = pk_h2(v1[0], v1[1]); w.w = pk_h2(v1[2], v1[3]);
;                     *(u32x4*)(out + ro + bj * HALF) = w; } }
;     }
	v_lshl_add_u64 v[184:185], v[184:185], 0, s[100:101]
	v_pk_fma_f32 v[80:81], v[80:81], v[132:133], v[112:113]
	v_pk_fma_f32 v[78:79], v[78:79], v[130:131], v[110:111]
	v_pk_fma_f32 v[76:77], v[76:77], v[144:145], v[108:109]
	v_pk_fma_f32 v[74:75], v[74:75], v[142:143], v[106:107]
	v_cvt_pk_f16_f32 v78, v78, v79
	v_cvt_pk_f16_f32 v79, v80, v81
	v_cvt_pk_f16_f32 v80, v74, v75
	v_cvt_pk_f16_f32 v81, v76, v77
	global_store_dwordx4 v[184:185], v[78:81], off
	v_pk_fma_f32 v[72:73], v[72:73], v[140:141], v[104:105]
	v_pk_fma_f32 v[70:71], v[70:71], v[138:139], v[102:103]
	v_pk_fma_f32 v[68:69], v[68:69], v[136:137], v[100:101]
	v_pk_fma_f32 v[66:67], v[66:67], v[134:135], v[98:99]
	v_cvt_pk_f16_f32 v70, v70, v71
	v_cvt_pk_f16_f32 v71, v72, v73
	v_cvt_pk_f16_f32 v72, v66, v67
	v_cvt_pk_f16_f32 v73, v68, v69
	global_store_dwordx4 v[184:185], v[70:73], off offset:256
	v_lshl_add_u64 v[182:183], v[182:183], 0, s[98:99]
	global_load_dwordx4 v[78:81], v[182:183], off
	global_load_dwordx4 v[74:77], v[182:183], off offset:16
	global_load_dwordx4 v[70:73], v[182:183], off offset:512
	global_load_dwordx4 v[66:69], v[182:183], off offset:528
	s_waitcnt vmcnt(6)
	v_lshl_add_u64 v[184:185], v[184:185], 0, s[100:101]
	v_lshl_add_u64 v[184:185], v[184:185], 0, s[100:101]
	v_lshl_add_u64 v[184:185], v[184:185], 0, s[100:101]
	v_lshl_add_u64 v[184:185], v[184:185], 0, s[100:101]
	v_lshl_add_u64 v[184:185], v[184:185], 0, s[100:101]
	v_pk_fma_f32 v[64:65], v[64:65], v[132:133], v[96:97]
	v_pk_fma_f32 v[62:63], v[62:63], v[130:131], v[94:95]
	v_pk_fma_f32 v[60:61], v[60:61], v[144:145], v[92:93]
	v_pk_fma_f32 v[58:59], v[58:59], v[142:143], v[90:91]
	v_cvt_pk_f16_f32 v62, v62, v63
	v_cvt_pk_f16_f32 v63, v64, v65
	v_cvt_pk_f16_f32 v64, v58, v59
	v_cvt_pk_f16_f32 v65, v60, v61
	global_store_dwordx4 v[184:185], v[62:65], off
	v_pk_fma_f32 v[56:57], v[56:57], v[140:141], v[88:89]
	v_pk_fma_f32 v[54:55], v[54:55], v[138:139], v[86:87]
	v_pk_fma_f32 v[52:53], v[52:53], v[136:137], v[84:85]
	v_pk_fma_f32 v[50:51], v[50:51], v[134:135], v[82:83]
	v_cvt_pk_f16_f32 v54, v54, v55
	v_cvt_pk_f16_f32 v55, v56, v57
	v_cvt_pk_f16_f32 v56, v50, v51
	v_cvt_pk_f16_f32 v57, v52, v53
	global_store_dwordx4 v[184:185], v[54:57], off offset:256
	v_lshl_add_u64 v[182:183], v[182:183], 0, s[98:99]
	global_load_dwordx4 v[62:65], v[182:183], off
	global_load_dwordx4 v[58:61], v[182:183], off offset:16
	global_load_dwordx4 v[54:57], v[182:183], off offset:512
	global_load_dwordx4 v[50:53], v[182:183], off offset:528
	s_waitcnt vmcnt(6)
	v_lshl_add_u64 v[184:185], v[184:185], 0, s[100:101]
	v_pk_fma_f32 v[48:49], v[48:49], v[132:133], v[80:81]
	v_pk_fma_f32 v[46:47], v[46:47], v[130:131], v[78:79]
	v_pk_fma_f32 v[44:45], v[44:45], v[144:145], v[76:77]
	v_pk_fma_f32 v[42:43], v[42:43], v[142:143], v[74:75]
	v_cvt_pk_f16_f32 v46, v46, v47
	v_cvt_pk_f16_f32 v47, v48, v49
	v_cvt_pk_f16_f32 v48, v42, v43
	v_cvt_pk_f16_f32 v49, v44, v45
	global_store_dwordx4 v[184:185], v[46:49], off
	v_pk_fma_f32 v[40:41], v[40:41], v[140:141], v[72:73]
	v_pk_fma_f32 v[38:39], v[38:39], v[138:139], v[70:71]
	v_pk_fma_f32 v[36:37], v[36:37], v[136:137], v[68:69]
	v_pk_fma_f32 v[34:35], v[34:35], v[134:135], v[66:67]
	v_cvt_pk_f16_f32 v38, v38, v39
	v_cvt_pk_f16_f32 v39, v40, v41
	v_cvt_pk_f16_f32 v40, v34, v35
	v_cvt_pk_f16_f32 v41, v36, v37
	global_store_dwordx4 v[184:185], v[38:41], off offset:256
	v_lshl_add_u64 v[182:183], v[182:183], 0, s[98:99]
	global_load_dwordx4 v[46:49], v[182:183], off
	global_load_dwordx4 v[42:45], v[182:183], off offset:16
	global_load_dwordx4 v[38:41], v[182:183], off offset:512
	global_load_dwordx4 v[34:37], v[182:183], off offset:528
	s_waitcnt vmcnt(6)
	v_lshl_add_u64 v[184:185], v[184:185], 0, s[100:101]
	v_pk_fma_f32 v[32:33], v[32:33], v[132:133], v[64:65]
	v_pk_fma_f32 v[30:31], v[30:31], v[130:131], v[62:63]
	v_pk_fma_f32 v[28:29], v[28:29], v[144:145], v[60:61]
	v_pk_fma_f32 v[26:27], v[26:27], v[142:143], v[58:59]
	v_cvt_pk_f16_f32 v30, v30, v31
	v_cvt_pk_f16_f32 v31, v32, v33
	v_cvt_pk_f16_f32 v32, v26, v27
	v_cvt_pk_f16_f32 v33, v28, v29
	global_store_dwordx4 v[184:185], v[30:33], off
	v_pk_fma_f32 v[24:25], v[24:25], v[140:141], v[56:57]
	v_pk_fma_f32 v[22:23], v[22:23], v[138:139], v[54:55]
	v_pk_fma_f32 v[20:21], v[20:21], v[136:137], v[52:53]
	v_pk_fma_f32 v[18:19], v[18:19], v[134:135], v[50:51]
	v_cvt_pk_f16_f32 v22, v22, v23
	v_cvt_pk_f16_f32 v23, v24, v25
	v_cvt_pk_f16_f32 v24, v18, v19
	v_cvt_pk_f16_f32 v25, v20, v21
	global_store_dwordx4 v[184:185], v[22:25], off offset:256
	s_waitcnt vmcnt(2)
	v_lshl_add_u64 v[184:185], v[184:185], 0, s[100:101]
	v_pk_fma_f32 v[16:17], v[16:17], v[132:133], v[48:49]
	v_pk_fma_f32 v[14:15], v[14:15], v[130:131], v[46:47]
	v_pk_fma_f32 v[12:13], v[12:13], v[144:145], v[44:45]
	v_pk_fma_f32 v[10:11], v[10:11], v[142:143], v[42:43]
	v_cvt_pk_f16_f32 v14, v14, v15
	v_cvt_pk_f16_f32 v15, v16, v17
	v_cvt_pk_f16_f32 v16, v10, v11
	v_cvt_pk_f16_f32 v17, v12, v13
	global_store_dwordx4 v[184:185], v[14:17], off
	v_pk_fma_f32 v[8:9], v[8:9], v[140:141], v[40:41]
	v_pk_fma_f32 v[6:7], v[6:7], v[138:139], v[38:39]
	v_pk_fma_f32 v[4:5], v[4:5], v[136:137], v[36:37]
	v_pk_fma_f32 v[2:3], v[2:3], v[134:135], v[34:35]
	v_cvt_pk_f16_f32 v6, v6, v7
	v_cvt_pk_f16_f32 v7, v8, v9
	v_cvt_pk_f16_f32 v8, v2, v3
	v_cvt_pk_f16_f32 v9, v4, v5
	global_store_dwordx4 v[184:185], v[6:9], off offset:256
	s_cbranch_vccnz .LBB0_704
	s_andn2_b64 vcc, exec, s[8:9]
	s_cbranch_vccnz .LBB0_703
	s_barrier
	s_branch .LBB0_703
